# v30: phase 0 converts only the HGRN weights; the other weight conversions are done by the 236 CUs idle in the last round of the two HGRN input GEMMs (re-entering the conversion loop before the grid ba
# baseline (speedup 1.0000x reference)
; #define PG8_LAS __attribute__((address_space(3)))
; #define LAS __attribute__((address_space(3)))
; __device__ __forceinline__ unsigned xb_add(unsigned* p, unsigned v) { return __hip_atomic_fetch_add(p, v, __ATOMIC_RELAXED, __HIP_MEMORY_SCOPE_AGENT); }
; __device__ __forceinline__ unsigned xb_xcc_id() { return (unsigned)__builtin_amdgcn_s_getreg((3 << 11) | 20) & 0xFu; }
; __device__ __forceinline__ XcdBarrier xcd_barrier_post(unsigned* bar, volatile LAS unsigned* st) {
;     XcdBarrier b; b.bar = bar; b.x = xb_xcc_id(); b.st = st;
;     if (threadIdx.x == 0) (void)xb_add(&bar[XB_XCNT(b.x)], 1u);
;     return b;
; }
; __device__ __forceinline__ void xcd_barrier_complete(unsigned* bar, unsigned x, unsigned& nloc, unsigned& nx) {
;     const unsigned G = gridDim.x * gridDim.y * gridDim.z;
; __global__ void __launch_bounds__(512, 2) fwd_mega(Args a_) {
;     ArgP ap0 = (ArgP)__builtin_amdgcn_kernarg_segment_ptr();
;     extern __shared__ __attribute__((aligned(16))) unsigned char lds[];
;     cg::grid_group grid = cg::this_grid();
;     PG8_LAS float* edge = (PG8_LAS float*)((PG8_LAS unsigned char*)lds + RING_BYTES);
;     volatile LAS unsigned* bst = (volatile LAS unsigned*)((LAS unsigned char*)lds + LDS_BYTES - 16);
;     const int wave_s = __builtin_amdgcn_readfirstlane(threadIdx.x >> 6);
;     if (threadIdx.x < 4) bst[threadIdx.x] = 0u;
;     __syncthreads();
;     XcdBarrier xbar = xcd_barrier_post((unsigned*)(ap0->ws + WS_BAR), bst);
;     grid.sync();
.LBB0_5:
	s_or_b64 exec, exec, s[6:7]
	v_lshrrev_b32_e32 v2, 20, v0
	v_lshrrev_b32_e32 v0, 10, v0
	v_or_b32_e32 v0, v0, v2
	s_movk_i32 s6, 0x3ff
	v_and_or_b32 v0, v0, s6, v1
	v_cmp_eq_u32_e32 vcc, 0, v0
	s_barrier
	s_and_b32 s84, s3, 0xffffffc0
	s_cmpk_lt_i32 s96, 0x104
	s_cselect_b64 s[6:7], -1, 0
	s_ashr_i32 s97, s96, 31
	s_lshr_b32 s3, s97, 29
	s_add_i32 s3, s96, s3
	s_ashr_i32 s85, s3, 3
	s_and_b32 s3, s3, -8
	s_sub_i32 s86, s96, s3
	s_lshl_b32 s3, s86, 5
	s_or_b32 s3, s3, 4
	s_ashr_i32 s87, s94, 31
	s_lshl_b32 s93, s96, 3
	s_lshl_b32 s80, s94, 3
	v_writelane_b32 v253, s6, 0
	s_cmpk_lt_i32 s96, 0x100
	v_mov_b32_e32 v196, 0x358637bd
	v_writelane_b32 v253, s7, 1
	s_cselect_b64 s[6:7], -1, 0
	v_writelane_b32 v253, s6, 2
	s_cmpk_lt_i32 s96, 0xb42
	v_mov_b32_e32 v197, 1
	v_writelane_b32 v253, s7, 3
	s_cselect_b64 s[6:7], -1, 0
	v_writelane_b32 v253, s6, 4
	v_mov_b32_e32 v199, 0x1200
	s_movk_i32 s64, 0x6000
	v_writelane_b32 v253, s7, 5
	s_mul_i32 s6, s86, 0x168
	s_or_b32 s6, s6, 2
	s_cmpk_lt_i32 s96, 0x514
	s_mul_i32 s7, s86, 0xa2
	s_cselect_b64 s[8:9], -1, 0
	s_add_i32 s7, s7, 4
	s_lshl_b32 s14, s96, 9
	s_add_u32 s54, s0, 0xb0200
	s_addc_u32 s55, s1, 0
	s_add_u32 s60, s0, 0xb0400
	s_addc_u32 s61, s1, 0
	s_add_u32 s12, s0, 0xb0500
	s_addc_u32 s13, s1, 0
	s_add_u32 s16, s0, 0xb0600
	s_addc_u32 s17, s1, 0
	s_add_u32 s62, s0, 0xb0700
	v_writelane_b32 v253, s8, 6
	s_addc_u32 s63, s1, 0
	s_mov_b32 s33, 0x800000
	v_writelane_b32 v253, s9, 7
	s_add_u32 s8, s0, 0xb0800
	s_addc_u32 s9, s1, 0
	v_writelane_b32 v253, s8, 8
	s_movk_i32 s82, 0x40ff
	s_movk_i32 s26, 0x407f
	v_writelane_b32 v253, s9, 9
	s_add_u32 s8, s0, 0xb0900
	s_addc_u32 s9, s1, 0
	v_writelane_b32 v253, s8, 10
	s_movk_i32 s27, 0xb00
	s_movk_i32 s90, 0x5800
	v_writelane_b32 v253, s9, 11
	s_add_u32 s8, s0, 0xb0a00
	s_addc_u32 s9, s1, 0
	v_writelane_b32 v253, s8, 12
	s_mov_b32 s83, 0
	s_mov_b32 s98, 0
	s_mov_b32 s25, 0
	v_writelane_b32 v253, s9, 13
	s_add_u32 s8, s0, 0xb0b00
	s_addc_u32 s9, s1, 0
	v_writelane_b32 v253, s8, 14
	s_mov_b64 s[28:29], 0x80
	s_mov_b32 s30, 0xbf1b4598
	v_writelane_b32 v253, s9, 15
	s_add_u32 s8, s0, 0xb0c00
	s_addc_u32 s9, s1, 0
	v_writelane_b32 v253, s8, 16
	s_mov_b64 s[34:35], 0x1200
	s_nop 0
	v_writelane_b32 v253, s9, 17
	s_add_u32 s8, s0, 0xb0d00
	s_addc_u32 s9, s1, 0
	v_writelane_b32 v253, s8, 18
	s_nop 1
	v_writelane_b32 v253, s9, 19
	s_add_u32 s8, s0, 0xb0e00
	s_addc_u32 s9, s1, 0
	v_writelane_b32 v253, s8, 20
	s_nop 1
	v_writelane_b32 v253, s9, 21
	s_add_u32 s8, s0, 0xb0f00
	s_addc_u32 s9, s1, 0
	v_writelane_b32 v253, s8, 22
	s_nop 1
	v_writelane_b32 v253, s9, 23
	s_add_u32 s8, s0, 0xb1000
	s_addc_u32 s9, s1, 0
	v_writelane_b32 v253, s8, 24
	s_nop 1
	v_writelane_b32 v253, s9, 25
	s_add_u32 s8, s0, 0xb1100
	s_addc_u32 s9, s1, 0
	v_writelane_b32 v253, s8, 26
	s_nop 1
	v_writelane_b32 v253, s9, 27
	s_add_u32 s8, s0, 0xb1200
	s_addc_u32 s9, s1, 0
	v_writelane_b32 v253, s8, 28
	s_nop 1
	v_writelane_b32 v253, s9, 29
	s_add_u32 s8, s0, 0xb1300
	s_addc_u32 s9, s1, 0
	v_writelane_b32 v253, s8, 30
	s_cmp_eq_u32 s2, 15
	s_nop 0
	v_writelane_b32 v253, s9, 31
	s_cselect_b64 s[8:9], -1, 0
	v_writelane_b32 v253, s8, 32
	s_cmp_eq_u32 s2, 14
	s_nop 0
	v_writelane_b32 v253, s9, 33
	s_cselect_b64 s[8:9], -1, 0
	v_writelane_b32 v253, s8, 34
	s_cmp_eq_u32 s2, 13
	s_nop 0
	v_writelane_b32 v253, s9, 35
	s_cselect_b64 s[8:9], -1, 0
	v_writelane_b32 v253, s8, 36
	s_cmp_eq_u32 s2, 12
	s_nop 0
	v_writelane_b32 v253, s9, 37
	s_cselect_b64 s[8:9], -1, 0
	v_writelane_b32 v253, s8, 38
	s_cmp_eq_u32 s2, 11
	s_nop 0
	v_writelane_b32 v253, s9, 39
	s_cselect_b64 s[8:9], -1, 0
	v_writelane_b32 v253, s8, 40
	s_cmp_eq_u32 s2, 10
	s_nop 0
	v_writelane_b32 v253, s9, 41
	s_cselect_b64 s[8:9], -1, 0
	v_writelane_b32 v253, s8, 42
	s_cmp_eq_u32 s2, 9
	s_nop 0
	v_writelane_b32 v253, s9, 43
	s_cselect_b64 s[8:9], -1, 0
	v_writelane_b32 v253, s8, 44
	s_cmp_eq_u32 s2, 8
	s_nop 0
	v_writelane_b32 v253, s9, 45
	s_cselect_b64 s[8:9], -1, 0
	v_writelane_b32 v253, s8, 46
	s_cmp_eq_u32 s2, 7
	s_nop 0
	v_writelane_b32 v253, s9, 47
	s_cselect_b64 s[8:9], -1, 0
	v_writelane_b32 v253, s8, 48
	s_cmp_eq_u32 s2, 6
	s_nop 0
	v_writelane_b32 v253, s9, 49
	s_cselect_b64 s[8:9], -1, 0
	v_writelane_b32 v253, s8, 50
	s_cmp_eq_u32 s2, 5
	s_nop 0
	v_writelane_b32 v253, s9, 51
	s_cselect_b64 s[8:9], -1, 0
	v_writelane_b32 v253, s8, 52
	s_cmp_eq_u32 s2, 4
	s_nop 0
	v_writelane_b32 v253, s9, 53
	s_cselect_b64 s[8:9], -1, 0
	v_writelane_b32 v253, s8, 54
	s_cmp_eq_u32 s2, 3
	s_nop 0
	v_writelane_b32 v253, s9, 55
	s_cselect_b64 s[8:9], -1, 0
	v_writelane_b32 v253, s8, 56
	s_cmp_eq_u32 s2, 2
	s_nop 0
	v_writelane_b32 v253, s9, 57
	s_cselect_b64 s[8:9], -1, 0
	v_writelane_b32 v253, s8, 58
	s_cmp_eq_u32 s2, 1
	s_nop 0
	v_writelane_b32 v253, s9, 59
	s_cselect_b64 s[8:9], -1, 0
	v_writelane_b32 v253, s8, 60
	s_cmp_eq_u32 s2, 0
	s_nop 0
	v_writelane_b32 v253, s9, 61
	s_cselect_b64 s[8:9], -1, 0
	s_lshl_b32 s2, s2, 8
	s_add_u32 s2, s4, s2
	v_writelane_b32 v253, s8, 62
	s_addc_u32 s4, s5, 0
	s_nop 0
	v_writelane_b32 v253, s9, 63
	s_add_u32 s8, s2, 0x1400
	s_addc_u32 s9, s4, 0
	v_writelane_b32 v254, s8, 0
	s_nop 1
	v_writelane_b32 v254, s9, 1
	s_add_u32 s8, s2, 0x2400
	s_addc_u32 s9, s4, 0
	v_writelane_b32 v254, s8, 2
	s_add_u32 s4, s0, 0xb3400
	s_addc_u32 s5, s1, 0
	v_writelane_b32 v254, s9, 3
	v_writelane_b32 v254, s4, 4
	s_add_u32 s0, s0, 0xb3500
	s_addc_u32 s1, s1, 0
	v_writelane_b32 v254, s5, 5
;     __host__ __device__ bool next(int i, Unit& u) const {
;         const long L = (long)i * G + c; if (L >= nwg) return false;
;         int wgid = (int)L; { const int q = nwg / NXCD, r = nwg % NXCD, xcd = wgid % NXCD, off = wgid / NXCD; wgid = (xcd < r ? xcd * (q + 1) : r * (q + 1) + (xcd - r) * q) + off; }
;         const int nig = WGM * nN, gid = wgid / nig, fm = gid * WGM, gsz = (nM - fm) < WGM ? (nM - fm) : WGM;
;         u.pm = fm + ((wgid % nig) % gsz); u.pn = (wgid % nig) / gsz; return true;
	v_writelane_b32 v254, s0, 6
	s_cmp_lt_i32 s86, 4
	s_nop 0
	v_writelane_b32 v254, s1, 7
	s_mul_i32 s0, s86, 33
	s_cselect_b32 s0, s0, s3
	s_mul_i32 s1, s86, 0xa3
	s_cselect_b32 s1, s1, s7
	s_add_i32 s0, s0, s85
	s_ashr_i32 s2, s0, 31
	s_lshr_b32 s2, s2, 27
	s_add_i32 s2, s0, s2
	s_and_b32 s3, s2, 0xffffffe0
	s_sub_i32 s3, s0, s3
	s_ashr_i32 s0, s2, 5
	s_lshl_b32 s2, s0, 3
	s_sub_i32 s0, 0x41, s2
	s_min_u32 s4, s0, 8
	s_cmp_lt_i32 s86, 2
	s_mul_i32 s0, s86, 0x169
	s_cselect_b32 s0, s0, s6
	s_add_i32 s0, s0, s85
	s_mul_hi_i32 s5, s0, 0x2e8ba2e9
	s_lshr_b32 s6, s5, 31
	s_ashr_i32 s5, s5, 5
	s_add_i32 s5, s5, s6
	v_cvt_f32_ubyte0_e32 v1, s4
	s_mul_i32 s6, s5, 0xb0
	s_add_i32 s1, s1, s85
	v_cvt_f32_i32_e32 v0, s3
	v_rcp_iflag_f32_e32 v2, v1
	s_sub_i32 s6, s0, s6
	s_mul_hi_i32 s0, s1, 0x66666667
	s_lshr_b32 s7, s0, 31
	s_ashr_i32 s0, s0, 6
	s_add_i32 s0, s0, s7
	s_lshl_b32 s9, s0, 3
	v_mul_f32_e32 v2, v0, v2
	s_mul_i32 s7, s0, 0xa0
	s_lshl_b32 s5, s5, 3
	s_sub_i32 s0, 0x41, s9
	v_trunc_f32_e32 v2, v2
	s_sub_i32 s7, s1, s7
	s_sub_i32 s1, 0x83, s5
	s_min_u32 s10, s0, 8
	s_ashr_i32 s0, s3, 30
	v_fma_f32 v0, -v2, v1, v0
	s_min_u32 s8, s1, 8
	s_or_b32 s11, s0, 1
	v_cmp_ge_f32_e64 s[0:1], |v0|, v1
	v_cvt_i32_f32_e32 v0, v2
	s_and_b64 s[0:1], s[0:1], exec
	s_cselect_b32 s0, s11, 0
	v_cvt_f32_ubyte0_e32 v1, s8
	v_readfirstlane_b32 s1, v0
	s_add_i32 s0, s1, s0
	s_mul_i32 s1, s0, s4
	v_cvt_f32_i32_e32 v0, s6
	v_rcp_iflag_f32_e32 v2, v1
	s_sub_i32 s1, s3, s1
	s_sext_i32_i8 s1, s1
	s_add_i32 s1, s2, s1
	s_sext_i32_i8 s3, s0
	s_ashr_i32 s0, s6, 30
	s_or_b32 s2, s0, 1
	v_mul_f32_e32 v2, v0, v2
	v_writelane_b32 v254, s1, 8
	s_ashr_i32 s0, s1, 31
	v_trunc_f32_e32 v2, v2
	v_writelane_b32 v254, s0, 9
	v_fma_f32 v0, -v2, v1, v0
	v_writelane_b32 v254, s3, 10
	s_ashr_i32 s0, s3, 31
	v_writelane_b32 v254, s0, 11
	v_cmp_ge_f32_e64 s[0:1], |v0|, v1
	v_cvt_i32_f32_e32 v0, v2
	s_and_b64 s[0:1], s[0:1], exec
	v_cvt_f32_ubyte0_e32 v1, s10
	s_cselect_b32 s0, s2, 0
	v_readfirstlane_b32 s1, v0
	v_cvt_f32_i32_e32 v0, s7
	v_rcp_iflag_f32_e32 v2, v1
	s_add_i32 s2, s1, s0
	s_mul_i32 s0, s2, s8
	s_sub_i32 s0, s6, s0
	s_sext_i32_i16 s0, s0
	v_mul_f32_e32 v2, v0, v2
	s_add_i32 s0, s5, s0
	v_trunc_f32_e32 v2, v2
	v_writelane_b32 v254, s0, 12
	s_ashr_i32 s0, s7, 30
	v_fma_f32 v0, -v2, v1, v0
	s_or_b32 s3, s0, 1
	v_cmp_ge_f32_e64 s[0:1], |v0|, v1
	s_and_b64 s[0:1], s[0:1], exec
	s_load_dword s1, s[78:79], 0x118
	v_cvt_i32_f32_e32 v0, v2
	s_mul_i32 s0, s95, s94
	s_mov_b32 s95, s14
	v_mov_b32_e32 v1, 0
	s_waitcnt lgkmcnt(0)
	s_mul_i32 s91, s0, s1
	s_cselect_b32 s0, s3, 0
	v_readfirstlane_b32 s1, v0
	s_add_i32 s0, s1, s0
	s_mul_i32 s1, s0, s10
	s_sub_i32 s1, s7, s1
	s_sext_i32_i16 s1, s1
	s_add_i32 s1, s9, s1
	v_writelane_b32 v254, s1, 13
	s_sext_i32_i16 s1, s2
	v_writelane_b32 v254, s1, 14
	s_sext_i32_i16 s0, s0
	v_writelane_b32 v254, s0, 15
	s_lshl_b32 s0, s96, 4
	v_writelane_b32 v254, s0, 16
	s_lshl_b32 s0, s96, 8
	v_writelane_b32 v254, s0, 17
	s_add_i32 s0, s93, 0xffffcc80
	v_writelane_b32 v254, s0, 18
	s_add_i32 s0, s93, 0xffffcd00
	v_writelane_b32 v254, s0, 19
	s_add_i32 s0, s93, 0xffffd300
	v_writelane_b32 v254, s0, 20
	s_add_i32 s0, s93, 0xffff7ec0
	v_writelane_b32 v254, s0, 21
	s_add_i32 s0, 0, 0x1c400
	v_writelane_b32 v254, s0, 22
	s_add_i32 s0, 0, 0x1d000
	v_writelane_b32 v254, s0, 23
	s_add_i32 s0, 0, 0x1ce00
	v_writelane_b32 v254, s0, 24
	s_add_i32 s0, 0, 0x1cc00
	v_writelane_b32 v254, s0, 25
	s_add_i32 s0, 0, 0x21d00
	v_writelane_b32 v254, s0, 26
	s_add_i32 s0, 0, 0x16800
	v_writelane_b32 v254, s0, 27
	s_add_i32 s0, 0, 0x14400
	v_writelane_b32 v254, s0, 28
	s_add_i32 s0, 0, 0x18c00
	v_writelane_b32 v254, s0, 29
	s_add_i32 s0, 0, 0x1b000
	v_writelane_b32 v254, s0, 30
	s_add_i32 s0, 0, 0x1d400
	v_writelane_b32 v254, s0, 31
	s_add_i32 s0, 0, 0x1f800
	v_writelane_b32 v254, s0, 32
	s_add_i32 s0, 0, 0x1a800
	v_writelane_b32 v254, s0, 33
	s_add_i32 s0, 0, 0x21c00
	v_writelane_b32 v254, s0, 34
	s_add_i32 s0, 0, 0x20800
	v_writelane_b32 v254, s0, 35
	s_add_i32 s0, 0, 0x20000
	v_writelane_b32 v254, s0, 36
	s_add_i32 s0, 0, 0x13c00
	v_writelane_b32 v254, s0, 37
	s_add_i32 s0, 0, 0x23ff0
	s_ashr_i32 s81, s80, 31
	v_writelane_b32 v254, s0, 38
	s_add_i32 s0, 0, 0x23ff4
	v_writelane_b32 v254, s0, 39
	s_lshl_b64 s[0:1], s[80:81], 6
	v_writelane_b32 v254, s0, 40
	v_writelane_b32 v255, s91, 0
	v_writelane_b32 v255, s12, 1
	v_writelane_b32 v254, s1, 41
	s_lshl_b64 s[0:1], s[80:81], 11
	v_writelane_b32 v254, s0, 42
	v_writelane_b32 v255, s13, 2
	v_mbcnt_lo_u32_b32 v0, -1, 0
	v_writelane_b32 v254, s1, 43
	s_lshl_b64 s[0:1], s[80:81], 12
	v_writelane_b32 v254, s0, 44
	v_writelane_b32 v255, s16, 3
	v_mbcnt_hi_u32_b32 v198, -1, v0
	v_writelane_b32 v254, s1, 45
	v_writelane_b32 v254, s78, 46
	s_mov_b32 s0, s94
	s_movk_i32 s3, 0x400
	v_writelane_b32 v254, s79, 47
	v_writelane_b32 v254, s0, 48
	s_movk_i32 s14, 0x203f
	v_writelane_b32 v255, s17, 4
	v_writelane_b32 v254, s1, 49
	v_writelane_b32 v254, s84, 50
	v_writelane_b32 v254, s85, 51
	v_writelane_b32 v254, s86, 52
	v_writelane_b32 v254, s87, 53
	v_writelane_b32 v254, s93, 54
	v_writelane_b32 v254, s80, 55
	s_barrier
	s_nop 0
	v_writelane_b32 v254, s81, 56
	v_writelane_b32 v254, s95, 57
	v_writelane_b32 v254, s54, 58
	s_nop 1
	v_writelane_b32 v254, s55, 59
	v_writelane_b32 v254, s60, 60
	s_nop 1
	v_writelane_b32 v254, s61, 61
	v_writelane_b32 v254, s62, 62
	s_nop 1
	v_writelane_b32 v254, s63, 63
	s_branch .LBB0_19

; __device__ __forceinline__ void p0_prologue(ArgP ap, unsigned char* lds, int tid) {
;     const int lane = tid & 63, wave = tid >> 6;
;     float* scr = (float*)(lds + wave * 16384);
;     int gdim = gridDim.x; asm volatile("" : "+s"(gdim));
;     const int gw = blockIdx.x * 8 + wave, NGW = gdim * 8;
;     unsigned char* dob = (unsigned char*)ap->out;
;     bf16* WHG = (bf16*)(dob + DO_WHG); bf16* WHGO = (bf16*)(dob + DO_WHGO); bf16* WF0I = (bf16*)(dob + DO_WF0I); bf16* WF0O = (bf16*)(dob + DO_WF0O);
;     bf16* WRW1 = (bf16*)(dob + DO_WRW1); bf16* WLORA = (bf16*)(dob + DO_WLORA); bf16* WRWO = (bf16*)(dob + DO_WRWO); bf16* WG2 = (bf16*)(dob + DO_WG2); bf16* WF1I = (bf16*)(dob + DO_WF1I); bf16* WF1O = (bf16*)(dob + DO_WF1O);
;     const float* mu = ap->in[10];
;     constexpr int I_HG = 16 * 160, I_SQ = 16 * 32, I_FI = 16 * 176, I_FO = 44 * 32, I_L64 = 16 * 2, I_G1 = 16 * 5, I_G2 = 4 * 32;
;     constexpr int NITEMS = I_HG + I_SQ + 2 * I_FI + 2 * I_FO + 3 * I_SQ + 4 * I_L64 + 4 * I_L64 + 2 * I_G1 + I_SQ + I_G2;
;     for (int it = gw; it < NITEMS; it += NGW) {
;         int r = it;
;         if (r < I_HG) { const int kb = r / 160, nb = r % 160; tr_item(ap->in[6], 5120, 1024, 64 * kb, 32 * nb, WHG, 1024, 32 * nb, 0, ap->in[3], scr, lane, nullptr, false); continue; } r -= I_HG;
.LBB0_753:
	s_andn2_b64 vcc, exec, s[0:1]
	s_cbranch_vccnz .LBB0_961
	s_movk_i32 s99, 0x3720
	s_mov_b32 s100, 0
	s_mov_b32 s101, s94
	s_cmp_lg_u32 s94, 0x100
	s_cbranch_scc1 .Ldefer_par_done
	s_movk_i32 s99, 0xc00
	s_cmp_eq_u32 s98, 0
	s_cbranch_scc1 .Ldefer_par_done
	s_mov_b32 s99, 0
	s_cmp_lt_u32 s96, 20
	s_cbranch_scc1 .Ldefer_par_done
	s_movk_i32 s101, 0xec
	s_movk_i32 s99, 0x2200
	s_movk_i32 s100, 0xb60
	s_cmp_eq_u32 s83, 1
	s_cbranch_scc1 .Ldefer_par_done
	s_movk_i32 s99, 0x3720
	s_movk_i32 s100, 0x2160
.Ldefer_par_done:
	s_mov_b32 s1, s101
	v_ashrrev_i32_e32 v13, 6, v202
	s_lshl_b32 s0, s1, 3
	s_waitcnt lgkmcnt(0)
	v_add_u32_e32 v18, s93, v13
	v_add_u32_e32 v18, s100, v18
	s_add_u32 s8, s4, 0x6380000
	s_mov_b32 s2, s99
	v_and_b32_e32 v11, 63, v203
	s_addc_u32 s9, s5, 0
	v_cmp_gt_i32_e32 vcc, s2, v18
	s_and_saveexec_b64 s[10:11], vcc
	s_cbranch_execz .LBB0_928
	v_readlane_b32 s12, v255, 5
	v_readlane_b32 s13, v255, 6
	s_load_dwordx2 s[12:13], s[12:13], 0x50
	v_and_b32_e32 v6, 7, v203
	v_lshlrev_b32_e32 v4, 14, v13
	s_waitcnt vmcnt(0)
	v_lshrrev_b32_e32 v29, 3, v11
	v_lshlrev_b32_e32 v0, 4, v6
	v_add_u32_e32 v5, 0, v4
	v_mul_u32_u24_e32 v7, 0x420, v6
	v_lshl_add_u64 v[2:3], s[4:5], 0, v[0:1]
	v_lshlrev_b32_e32 v0, 2, v29
	s_mov_b64 s[20:21], 0x5d80000
	v_readlane_b32 s2, v254, 16
	s_mov_b64 s[16:17], 0x6e80000
	v_add3_u32 v52, v5, v7, v0
	v_lshlrev_b32_e32 v0, 5, v6
	v_lshl_add_u64 v[20:21], v[2:3], 0, s[20:21]
	s_mov_b64 s[20:21], 0x4b00000
	v_lshl_add_u32 v58, v13, 1, s2
	v_readlane_b32 s2, v254, 17
	v_lshrrev_b32_e32 v19, 5, v11
	v_lshl_add_u64 v[14:15], v[2:3], 0, s[16:17]
	s_mov_b64 s[16:17], 0x6c80000
	s_waitcnt lgkmcnt(0)
	s_cmp_lg_u64 s[12:13], 0
	v_lshl_add_u64 v[22:23], v[2:3], 0, s[20:21]
	s_mov_b64 s[20:21], 0x4100000
	v_lshl_add_u32 v59, v13, 5, s2
	v_readlane_b32 s2, v254, 18
	v_lshl_add_u64 v[30:31], s[12:13], 0, v[0:1]
	s_mov_b64 s[12:13], 0x5000
	v_and_b32_e32 v10, 31, v203
	v_lshl_add_u64 v[16:17], v[2:3], 0, s[16:17]
	v_lshl_add_u64 v[24:25], v[2:3], 0, s[20:21]
	v_mul_u32_u24_e32 v2, 0x84, v19
	v_add_u32_e32 v82, s2, v13
	v_readlane_b32 s2, v254, 19
	v_lshl_add_u64 v[32:33], v[30:31], 0, s[12:13]
	s_mov_b64 s[12:13], 0x4000
	v_or_b32_e32 v2, v4, v2
	v_lshlrev_b32_e32 v26, 2, v10
	v_add_u32_e32 v83, s2, v13
	v_readlane_b32 s2, v254, 20
	v_lshl_add_u64 v[34:35], v[30:31], 0, s[12:13]
	s_mov_b64 s[12:13], 0x1000
	v_lshlrev_b32_e32 v12, 3, v6
	v_or_b32_e32 v53, 8, v29
	v_or_b32_e32 v54, 16, v29
	v_or_b32_e32 v55, 24, v29
	s_mov_b64 s[16:17], 0
	s_cselect_b64 s[18:19], -1, 0
	v_add3_u32 v56, v2, v26, 0
	v_mov_b32_e32 v27, v1
	v_or_b32_e32 v57, 0xffff92ce, v19
	s_lshl_b32 s24, s1, 4
	s_lshl_b32 s54, s1, 8
	v_or_b32_e32 v60, 0xffff92cc, v19
	v_or_b32_e32 v61, 0xffff92ca, v19
	v_or_b32_e32 v62, 0xffff92c8, v19
	v_or_b32_e32 v63, 0xffff92c6, v19
	v_or_b32_e32 v64, 0xffff92c4, v19
	v_or_b32_e32 v65, 0xffff92c2, v19
	v_or_b32_e32 v66, 0xffff92c0, v19
	v_or_b32_e32 v67, 0xffff96ce, v19
	v_or_b32_e32 v68, 0xffff96cc, v19
	v_or_b32_e32 v69, 0xffff96ca, v19
	v_or_b32_e32 v70, 0xffff96c8, v19
	v_or_b32_e32 v71, 0xffff96c6, v19
	v_or_b32_e32 v72, 0xffff96c4, v19
	v_or_b32_e32 v73, 0xffff96c2, v19
	v_or_b32_e32 v74, 0xffff96c0, v19
	v_or_b32_e32 v75, 14, v19
	v_or_b32_e32 v76, 12, v19
	v_or_b32_e32 v77, 10, v19
	v_or_b32_e32 v78, 8, v19
	v_or_b32_e32 v79, 6, v19
	v_or_b32_e32 v80, 4, v19
	v_or_b32_e32 v81, 2, v19
	v_add_lshl_u32 v84, s2, v13, 1
	v_or_b32_e32 v85, 0xffffec0e, v19
	v_or_b32_e32 v86, 0xffffec0c, v19
	v_or_b32_e32 v87, 0xffffec0a, v19
	v_or_b32_e32 v88, 0xffffec08, v19
	v_or_b32_e32 v89, 0xffffec06, v19
	v_or_b32_e32 v90, 0xffffec04, v19
	v_or_b32_e32 v91, 0xffffec02, v19
	v_or_b32_e32 v92, 0xffffec00, v19
	v_bfe_u32 v28, v203, 5, 1
	v_mov_b32_e32 v93, v18
	v_lshl_add_u64 v[36:37], v[30:31], 0, s[12:13]
	s_lshl_b32 s2, s100, 1
	v_add_u32_e32 v58, s2, v58
	v_add_u32_e32 v84, s2, v84
	s_lshl_b32 s2, s100, 5
	v_add_u32_e32 v59, s2, v59
	v_add_u32_e32 v82, s100, v82
	v_add_u32_e32 v83, s100, v83
	s_branch .LBB0_759

; __device__ __forceinline__ void p0_prologue(ArgP ap, unsigned char* lds, int tid) {
;     ...
;     for (int it = gw; it < NITEMS; it += NGW) {
.LBB0_758:
	s_or_b64 exec, exec, s[20:21]
	v_add_u32_e32 v93, s0, v93
	s_add_i32 s2, s99, -1
	v_cmp_lt_i32_e32 vcc, s2, v93
	v_add_u32_e32 v58, s24, v58
	v_add_u32_e32 v59, s54, v59
	v_add_u32_e32 v82, s0, v82
	v_add_u32_e32 v83, s0, v83
	s_or_b64 s[16:17], vcc, s[16:17]
	v_add_u32_e32 v84, s24, v84
	s_andn2_b64 exec, exec, s[16:17]
	s_cbranch_execz .LBB0_928

; __device__ __forceinline__ void p0_prologue(ArgP ap, unsigned char* lds, int tid) {
;     ...
;     {
;         const int gt = blockIdx.x * 512 + tid, NGT = gdim * 512;
;         for (int i = gt; i < 96 * 256; i += NGT) { const int rr = i >> 8, cc = i & 255;
;             unsigned zz = 0u; asm volatile("" : "+v"(zz)); *(u32x4_t*)(WLORA + (size_t)(416 + rr) * 2048 + cc * 8) = (u32x4_t){zz, zz, zz, zz}; }
;     }
.LBB0_928:
	s_or_b64 exec, exec, s[10:11]
	s_cmp_eq_u32 s98, 1
	s_cbranch_scc0 .Ldefer_cont
	v_readlane_b32 s54, v254, 58
	v_readlane_b32 s55, v254, 59
	s_branch .LBB0_961
.Ldefer_cont:
	v_add_u32_e32 v2, s95, v202
	v_cmp_gt_i32_e32 vcc, s64, v2
	s_and_saveexec_b64 s[10:11], vcc
	s_cbranch_execz .LBB0_931
	s_lshl_b32 s2, s1, 9
	v_lshlrev_b32_e32 v3, 3, v2
	s_lshl_b32 s1, s1, 12
	s_mov_b64 s[12:13], 0

; __global__ void __launch_bounds__(512, 2) fwd_mega(Args a_) {
;     ...
;         int kind = 15, slab = 0;
;         if (ph == 0) kind = 0;
;         else if (ph <= 10) { const int q = (ph - 1) % 5; slab = (ph - 1) / 5; kind = q == 0 ? 1 : (q == 1 ? 14 : (q == 2 ? 2 : (q == 3 ? 3 : 4))); }
;         else if (ph == 11) kind = 5; else if (ph == 12) kind = 6;
;         else if (ph <= 26) { kind = 7 + (ph - 13) % 7; slab = (ph - 13) / 7; }
;         else if (ph == 27) { kind = 5; slab = 1; } else if (ph == 28) { kind = 6; slab = 1; }
;     ...
;         default: if (PHM & 2048) final_norm((const bf16*)(ws + WS_HBNEW), (const float*)(ws + WS_PB), ap->in[5], ap->out, tid); break;
;         }
;         if (phc < 29) { unsigned z2 = 0u; asm volatile("" : "+v"(z2)); const int t2 = wave_s * 64 + (int)__builtin_amdgcn_mbcnt_hi(~0u, __builtin_amdgcn_mbcnt_lo(~0u, z2)); xcd_barrier(xbar, t2); }
.LBB0_961:
	s_cmp_eq_u32 s98, 1
	s_cbranch_scc1 .Ldefer_back
	s_cmp_lg_u32 s94, 0x100
	s_cbranch_scc1 .Ldefer_none
	s_cmp_eq_u32 s83, 1
	s_cbranch_scc1 .Ldefer_go
	s_cmp_eq_u32 s83, 6
	s_cbranch_scc0 .Ldefer_none
.Ldefer_go:
	s_mov_b32 s98, 1
	s_mov_b32 s65, 0
	s_mov_b32 s40, 0
	s_branch .Ltramp_b50
.Ldefer_back:
	s_mov_b32 s98, 0
